# GEMM prologue de-serialised: all seven LDS-DMA stages of the first unit issued before the first counted wait (vmcnt 10 then 6)
# baseline (speedup 1.0000x reference)
; #define PG8_STAGE(bufoff, gbase, voff) do { _Pragma("unroll") for (int _i = 0; _i < 2; ++_i) \
;         __builtin_amdgcn_global_load_lds((const unsigned*)((const char*)(gbase) + (voff)[_i]), (LAS unsigned*)(lds + (bufoff) + ldsw + _i * 8192), 16, 0, 0); } while (0)
; #define PG8_WAIT_V(n) asm volatile("s_waitcnt vmcnt(" #n ")" ::: "memory")
; #define PG8_BAR __builtin_amdgcn_s_barrier()
; template <class Epi>
; __device__ __forceinline__ void gemm_phase(LAS unsigned char* lds, const Gemm g, const Epi& E) {
;     ...
;     f32x4 acc[2][2][4][2];
; #pragma unroll
;     for (int a = 0; a < 2; ++a)
; #pragma unroll
;         for (int b = 0; b < 2; ++b)
; #pragma unroll
;             for (int m = 0; m < 4; ++m)
; #pragma unroll
;                 for (int n = 0; n < 2; ++n) acc[a][b][m][n] = (f32x4){0.f, 0.f, 0.f, 0.f};
;     ...
;     const char* cA = (const char*)g.A + (size_t)cur.pm * tstepA; const char* cB = (const char*)g.Bt + (size_t)cur.pn * tstepB;
;     PG8_STAGE(PG8_SB(0, 0), cB, voffB); PG8_STAGE(PG8_SA(0, 0), cA, voffA); PG8_STAGE(PG8_SB(0, 1), cB + hstepB, voffB); PG8_STAGE(PG8_SA(0, 1), cA + hstepA, voffA);
;     if (wr == 1) PG8_BAR;
;     PG8_WAIT_V(4); PG8_BAR;
;     PG8_STAGE(PG8_SB(1, 0), cB + kstep, voffB); PG8_STAGE(PG8_SA(1, 0), cA + kstep, voffA); PG8_STAGE(PG8_SB(1, 1), cB + hstepB + kstep, voffB);
;     PG8_WAIT_V(6); PG8_BAR;
.LBB0_264:
	s_add_i32 m0, s8, 0x18000
	v_lshl_add_u64 v[12:13], v[12:13], 0, s[36:37]
	global_load_lds_dwordx4 v[12:13], off
	v_lshl_add_u64 v[10:11], v[10:11], 0, s[36:37]
	s_add_i32 m0, s8, 0x1a000
	s_add_i32 s38, s8, 0x8000
	global_load_lds_dwordx4 v[10:11], off
	v_lshl_add_u64 v[8:9], v[8:9], 0, s[36:37]
	s_mov_b32 m0, s38
	s_add_i32 s39, s8, 0xa000
	global_load_lds_dwordx4 v[8:9], off
	v_lshl_add_u64 v[6:7], v[6:7], 0, s[36:37]
	s_mov_b32 m0, s39
	v_lshl_add_u64 v[4:5], v[4:5], 0, s[36:37]
	global_load_lds_dwordx4 v[6:7], off
	s_add_i32 m0, s8, 0x1c000
	v_lshl_add_u64 v[2:3], v[2:3], 0, s[36:37]
	global_load_lds_dwordx4 v[4:5], off
	s_add_i32 m0, s8, 0x1e000
	v_bfe_u32 v14, v0, 4, 2
	global_load_lds_dwordx4 v[2:3], off
	s_waitcnt vmcnt(10)
	s_barrier
	v_and_b32_e32 v195, 15, v0
	v_lshlrev_b32_e32 v16, 4, v14
	v_lshlrev_b32_e32 v0, 2, v0
	s_and_b32 s4, s12, 3
	v_lshl_or_b32 v2, v195, 6, v16
	s_lshl_b32 s12, s5, 13
	v_and_b32_e32 v0, 32, v0
	v_bitop3_b32 v4, v2, s12, v0 bitop3:0xde
	s_lshl_b32 s12, s4, 12
	v_bitop3_b32 v197, v2, s12, v0 bitop3:0xde
	s_lshl_b32 s84, s10, 3
	v_lshlrev_b32_e32 v0, 2, v14
	v_lshl_or_b32 v199, s4, 4, v0
	v_cvt_f32_u32_e32 v0, s84
	s_lshr_b32 s87, s11, 6
	s_cmp_eq_u32 s53, 3
	s_cselect_b32 s87, 2, s87
	s_lshl_b32 s40, s11, 1
	s_lshr_b32 s11, s28, 3
	v_rcp_iflag_f32_e32 v0, v0
	v_lshl_or_b32 v196, s5, 6, v195
	v_lshlrev_b32_e32 v15, 3, v14
	v_writelane_b32 v249, s11, 59
	v_mul_f32_e32 v0, 0x4f7ffffe, v0
	v_cvt_u32_f32_e32 v0, v0
	s_mul_i32 s5, s5, 62
	v_writelane_b32 v249, s5, 60
	v_lshl_or_b32 v204, s4, 5, v15
	s_sub_i32 s4, 0, s84
	v_readfirstlane_b32 s5, v0
	s_waitcnt vmcnt(6)
	s_add_i32 s55, s11, 1
	v_cmp_ne_u32_e64 s[10:11], 0, v195
	s_mul_i32 s4, s4, s5
	v_mov_b32_e32 v2, v1
	v_mov_b32_e32 v3, v1
	v_cndmask_b32_e64 v198, 0, 1, s[92:93]
	v_writelane_b32 v249, s10, 61
	s_mul_hi_u32 s4, s5, s4
	v_mov_b32_e32 v0, v1
	v_add_u32_e32 v205, 0, v4
	v_mov_b64_e32 v[34:35], v[2:3]
	v_mov_b64_e32 v[30:31], v[2:3]
	v_mov_b64_e32 v[26:27], v[2:3]
	v_mov_b64_e32 v[22:23], v[2:3]
	v_mov_b64_e32 v[18:19], v[2:3]
	v_mov_b64_e32 v[14:15], v[2:3]
	v_mov_b64_e32 v[10:11], v[2:3]
	v_mov_b64_e32 v[6:7], v[2:3]
	v_mov_b64_e32 v[46:47], v[2:3]
	v_mov_b64_e32 v[42:43], v[2:3]
	v_mov_b64_e32 v[38:39], v[2:3]
	v_mov_b64_e32 v[130:131], v[2:3]
	v_mov_b64_e32 v[126:127], v[2:3]
	v_mov_b64_e32 v[122:123], v[2:3]
	v_mov_b64_e32 v[118:119], v[2:3]
	v_mov_b64_e32 v[114:115], v[2:3]
	v_mov_b64_e32 v[110:111], v[2:3]
	v_mov_b64_e32 v[106:107], v[2:3]
	v_mov_b64_e32 v[102:103], v[2:3]
	v_mov_b64_e32 v[98:99], v[2:3]
	v_mov_b64_e32 v[94:95], v[2:3]
	v_mov_b64_e32 v[90:91], v[2:3]
	v_mov_b64_e32 v[86:87], v[2:3]
	v_mov_b64_e32 v[82:83], v[2:3]
	v_mov_b64_e32 v[78:79], v[2:3]
	v_mov_b64_e32 v[74:75], v[2:3]
	v_mov_b64_e32 v[70:71], v[2:3]
	v_mov_b64_e32 v[66:67], v[2:3]
	v_mov_b64_e32 v[62:63], v[2:3]
	v_mov_b64_e32 v[58:59], v[2:3]
	v_mov_b64_e32 v[54:55], v[2:3]
	v_mov_b64_e32 v[50:51], v[2:3]
	s_ashr_i32 s41, s51, 31
	v_readfirstlane_b32 s42, v198
	s_ashr_i32 s43, s50, 31
	s_and_b32 s45, s28, 6
	s_add_i32 s85, s87, -2
	s_mov_b32 s16, 0
	v_writelane_b32 v249, s11, 62
	v_or_b32_e32 v200, 16, v195
	v_or_b32_e32 v201, 32, v195
	v_or_b32_e32 v202, 48, v195
	v_cmp_ne_u32_e64 s[10:11], 15, v195
	v_lshlrev_b32_e32 v203, 9, v196
	s_add_i32 s90, s5, s4
	v_lshl_add_u64 v[172:173], s[34:35], 0, v[164:165]
	v_lshl_add_u64 v[174:175], s[34:35], 0, v[168:169]
	v_mov_b64_e32 v[32:33], v[0:1]
	v_mov_b64_e32 v[28:29], v[0:1]
	v_mov_b64_e32 v[24:25], v[0:1]
	v_mov_b64_e32 v[20:21], v[0:1]
	v_mov_b64_e32 v[16:17], v[0:1]
	v_mov_b64_e32 v[12:13], v[0:1]
	v_mov_b64_e32 v[8:9], v[0:1]
	v_mov_b64_e32 v[4:5], v[0:1]
	v_mov_b64_e32 v[44:45], v[0:1]
	v_mov_b64_e32 v[40:41], v[0:1]
	v_mov_b64_e32 v[36:37], v[0:1]
	s_mov_b32 s91, 0
	v_mov_b64_e32 v[128:129], v[0:1]
	v_mov_b64_e32 v[124:125], v[0:1]
	v_mov_b64_e32 v[120:121], v[0:1]
	v_mov_b64_e32 v[116:117], v[0:1]
	v_mov_b64_e32 v[112:113], v[0:1]
	v_mov_b64_e32 v[108:109], v[0:1]
	v_mov_b64_e32 v[104:105], v[0:1]
	v_mov_b64_e32 v[100:101], v[0:1]
	v_mov_b64_e32 v[96:97], v[0:1]
	v_mov_b64_e32 v[92:93], v[0:1]
	v_mov_b64_e32 v[88:89], v[0:1]
	v_mov_b64_e32 v[84:85], v[0:1]
	v_mov_b64_e32 v[80:81], v[0:1]
	v_mov_b64_e32 v[76:77], v[0:1]
	v_mov_b64_e32 v[72:73], v[0:1]
	v_mov_b64_e32 v[68:69], v[0:1]
	v_mov_b64_e32 v[64:65], v[0:1]
	v_mov_b64_e32 v[60:61], v[0:1]
	v_mov_b64_e32 v[56:57], v[0:1]
	v_mov_b64_e32 v[52:53], v[0:1]
	v_mov_b64_e32 v[48:49], v[0:1]
	s_barrier
	v_writelane_b32 v249, s10, 63
	s_nop 1
	v_writelane_b32 v248, s11, 0
	s_branch .LBB0_267
